# latent attention: previous tile's row-sum chain and running-sum update interleaved between the dependent QK MFMAs; staging ds_writes moved to mid-tile
# speedup vs baseline: 1.0090x; 1.0032x over previous
.LBB0_370:
	s_or_b64 exec, exec, s[2:3]
	s_lshl_b32 s44, s17, 6
	v_or_b32_e32 v0, s44, v147
	v_mul_u32_u24_e32 v0, 0x3400, v0
	v_readlane_b32 s2, v250, 6
	v_lshlrev_b32_e32 v0, 1, v0
	v_readlane_b32 s3, v250, 7
	s_ashr_i32 s17, s16, 31
	v_lshlrev_b32_e32 v118, 1, v122
	v_lshl_add_u64 v[142:143], s[2:3], 0, v[0:1]
	v_lshl_add_u64 v[94:95], s[16:17], 1, v[142:143]
	v_mov_b32_e32 v119, v1
	v_lshl_add_u64 v[94:95], v[94:95], 0, v[118:119]
	global_load_dwordx4 v[94:97], v[94:95], off
	s_waitcnt vmcnt(0)
	ds_write_b128 v157, v[70:73]
	s_and_saveexec_b64 s[2:3], s[0:1]
	ds_write_b128 v158, v[66:69]
	s_or_b64 exec, exec, s[2:3]
	s_waitcnt lgkmcnt(0)
	v_add_f32_e32 v0, v167, v168
	v_fmamk_f32 v0, v0, 0x3c2aaaab, v248
	v_rsq_f32_e32 v0, v0
	s_mov_b32 s15, s4
	s_addk_i32 s45, 0x2800
	s_mov_b32 s17, 0
	v_mul_f32_e32 v0, 0x3e16c740, v0
	v_mul_f32_e32 v39, v39, v0
	v_mul_f32_e32 v38, v38, v0
	v_mul_f32_e32 v70, v40, v0
	v_mul_f32_e32 v40, v39, v163
	v_mul_f32_e32 v39, v41, v0
	v_mul_f32_e32 v34, v34, v0
	v_mul_f32_e32 v35, v35, v0
	v_mul_f32_e32 v38, v38, v162
	v_mul_f32_e32 v72, v39, v161
	v_mul_f32_e32 v34, v34, v160
	v_mul_f32_e32 v160, v35, v127
	v_mul_f32_e32 v35, v36, v0
	v_mul_f32_e32 v30, v30, v0
	v_pk_mul_f32 v[40:41], v[14:15], v[40:41] op_sel:[1,0] op_sel_hi:[0,0]
	v_mul_f32_e32 v70, v70, v164
	v_mul_f32_e32 v36, v35, v125
	v_mul_f32_e32 v35, v37, v0
	v_mul_f32_e32 v30, v30, v166
	v_mul_f32_e32 v31, v31, v0
	v_pk_fma_f32 v[166:167], v[14:15], v[38:39], v[40:41] neg_lo:[0,0,1] neg_hi:[0,0,1]
	v_pk_fma_f32 v[14:15], v[14:15], v[38:39], v[40:41] op_sel_hi:[1,0,1]
	v_pk_mul_f32 v[38:39], v[16:17], v[72:73] op_sel:[1,0] op_sel_hi:[0,0]
	v_mul_f32_e32 v162, v35, v113
	v_mul_f32_e32 v164, v31, v165
	v_mul_f32_e32 v31, v32, v0
	v_pk_fma_f32 v[40:41], v[16:17], v[70:71], v[38:39] neg_lo:[0,0,1] neg_hi:[0,0,1]
	v_pk_fma_f32 v[16:17], v[16:17], v[70:71], v[38:39] op_sel_hi:[1,0,1]
	v_pk_mul_f32 v[38:39], v[160:161], v[10:11] op_sel:[0,1] op_sel_hi:[0,0]
	v_mul_f32_e32 v32, v31, v79
	v_mul_f32_e32 v31, v33, v0
	v_mul_f32_e32 v27, v27, v0
	v_pk_fma_f32 v[160:161], v[34:35], v[10:11], v[38:39] neg_lo:[0,0,1] neg_hi:[0,0,1]
	v_pk_fma_f32 v[10:11], v[34:35], v[10:11], v[38:39] op_sel_hi:[0,1,1]
	v_pk_mul_f32 v[34:35], v[162:163], v[12:13] op_sel:[0,1] op_sel_hi:[0,0]
	v_mul_f32_e32 v78, v31, v78
	v_mul_f32_e32 v76, v27, v76
	v_mul_f32_e32 v27, v28, v0
	v_pk_fma_f32 v[38:39], v[36:37], v[12:13], v[34:35] neg_lo:[0,0,1] neg_hi:[0,0,1]
	v_pk_fma_f32 v[12:13], v[36:37], v[12:13], v[34:35] op_sel_hi:[0,1,1]
	v_pk_mul_f32 v[34:35], v[164:165], v[6:7] op_sel:[0,1] op_sel_hi:[0,0]
	v_mul_f32_e32 v26, v26, v0
	v_mul_f32_e32 v28, v27, v75
	v_mul_f32_e32 v27, v29, v0
	v_pk_fma_f32 v[36:37], v[30:31], v[6:7], v[34:35] neg_lo:[0,0,1] neg_hi:[0,0,1]
	v_pk_fma_f32 v[6:7], v[30:31], v[6:7], v[34:35] op_sel_hi:[0,1,1]
	v_pk_mul_f32 v[30:31], v[78:79], v[8:9] op_sel:[0,1] op_sel_hi:[0,0]
	v_mul_f32_e32 v26, v26, v77
	v_mul_f32_e32 v74, v27, v74
	v_pk_fma_f32 v[34:35], v[32:33], v[8:9], v[30:31] neg_lo:[0,0,1] neg_hi:[0,0,1]
	v_pk_fma_f32 v[8:9], v[32:33], v[8:9], v[30:31] op_sel_hi:[0,1,1]
	v_pk_mul_f32 v[30:31], v[76:77], v[2:3] op_sel:[0,1] op_sel_hi:[0,0]
	v_pk_fma_f32 v[32:33], v[26:27], v[2:3], v[30:31] neg_lo:[0,0,1] neg_hi:[0,0,1]
	v_pk_fma_f32 v[2:3], v[26:27], v[2:3], v[30:31] op_sel_hi:[0,1,1]
	v_pk_mul_f32 v[26:27], v[74:75], v[4:5] op_sel:[0,1] op_sel_hi:[0,0]
	v_pk_fma_f32 v[30:31], v[28:29], v[4:5], v[26:27] neg_lo:[0,0,1] neg_hi:[0,0,1]
	v_pk_fma_f32 v[4:5], v[28:29], v[4:5], v[26:27] op_sel_hi:[0,1,1]
	v_pk_mul_f32 v[24:25], v[24:25], v[0:1] op_sel_hi:[1,0]
	v_pk_mul_f32 v[22:23], v[22:23], v[0:1] op_sel_hi:[1,0]
	v_pk_mul_f32 v[20:21], v[20:21], v[0:1] op_sel_hi:[1,0]
	v_pk_mul_f32 v[18:19], v[18:19], v[0:1] op_sel_hi:[1,0]
	v_pk_mul_f32 v[26:27], v[48:49], v[0:1] op_sel_hi:[1,0]
	v_pk_mul_f32 v[28:29], v[46:47], v[0:1] op_sel_hi:[1,0]
	v_pk_mul_f32 v[44:45], v[44:45], v[0:1] op_sel_hi:[1,0]
	v_pk_mul_f32 v[42:43], v[42:43], v[0:1] op_sel_hi:[1,0]
	v_pk_mul_f32 v[46:47], v[56:57], v[0:1] op_sel_hi:[1,0]
	v_pk_mul_f32 v[48:49], v[54:55], v[0:1] op_sel_hi:[1,0]
	v_pk_mul_f32 v[52:53], v[52:53], v[0:1] op_sel_hi:[1,0]
	v_pk_mul_f32 v[50:51], v[50:51], v[0:1] op_sel_hi:[1,0]
	v_pk_mul_f32 v[54:55], v[64:65], v[0:1] op_sel_hi:[1,0]
	v_pk_mul_f32 v[56:57], v[62:63], v[0:1] op_sel_hi:[1,0]
	v_pk_mul_f32 v[60:61], v[60:61], v[0:1] op_sel_hi:[1,0]
	v_pk_mul_f32 v[58:59], v[58:59], v[0:1] op_sel_hi:[1,0]
	v_pk_mul_f32 v[24:25], v[24:25], v[80:81]
	v_pk_mul_f32 v[22:23], v[22:23], v[82:83]
	v_pk_mul_f32 v[20:21], v[20:21], v[84:85]
	v_pk_mul_f32 v[18:19], v[18:19], v[86:87]
	v_pk_mul_f32 v[26:27], v[26:27], v[88:89]
	v_pk_mul_f32 v[28:29], v[28:29], v[90:91]
	v_pk_mul_f32 v[44:45], v[44:45], v[92:93]
	v_pk_mul_f32 v[42:43], v[42:43], v[98:99]
	v_pk_mul_f32 v[46:47], v[46:47], v[100:101]
	v_pk_mul_f32 v[48:49], v[48:49], v[128:129]
	v_pk_mul_f32 v[52:53], v[52:53], v[130:131]
	v_pk_mul_f32 v[50:51], v[50:51], v[132:133]
	v_pk_mul_f32 v[54:55], v[54:55], v[134:135]
	v_pk_mul_f32 v[56:57], v[56:57], v[136:137]
	v_pk_mul_f32 v[60:61], v[60:61], v[138:139]
	v_pk_mul_f32 v[58:59], v[58:59], v[140:141]
	v_mov_b32_e32 v113, 0
	v_cvt_pk_bf16_f32 v70, v58, v59
	v_cvt_pk_bf16_f32 v71, v60, v61
	v_cvt_pk_bf16_f32 v72, v56, v57
	v_cvt_pk_bf16_f32 v73, v54, v55
	v_cvt_pk_bf16_f32 v74, v50, v51
	v_cvt_pk_bf16_f32 v75, v52, v53
	v_cvt_pk_bf16_f32 v76, v48, v49
	v_cvt_pk_bf16_f32 v77, v46, v47
	v_cvt_pk_bf16_f32 v78, v42, v43
	v_cvt_pk_bf16_f32 v79, v44, v45
	v_cvt_pk_bf16_f32 v80, v28, v29
	v_cvt_pk_bf16_f32 v81, v26, v27
	v_cvt_pk_bf16_f32 v82, v18, v19
	v_cvt_pk_bf16_f32 v83, v20, v21
	v_cvt_pk_bf16_f32 v84, v22, v23
	v_cvt_pk_bf16_f32 v85, v24, v25
	v_cvt_pk_bf16_f32 v86, v166, v15
	v_cvt_pk_bf16_f32 v87, v40, v17
	v_cvt_pk_bf16_f32 v88, v160, v11
	v_cvt_pk_bf16_f32 v89, v38, v13
	v_cvt_pk_bf16_f32 v90, v36, v7
	v_cvt_pk_bf16_f32 v91, v34, v9
	v_cvt_pk_bf16_f32 v92, v32, v3
	v_cvt_pk_bf16_f32 v93, v30, v5
	v_lshl_add_u64 v[64:65], v[106:107], 0, s[14:15]
	v_lshl_add_u64 v[128:129], v[110:111], 0, s[14:15]
	v_lshl_add_u64 v[130:131], v[142:143], 0, v[118:119]
	v_mov_b32_e32 v117, 0xf149f2ca
	s_mov_b32 s16, s38
	v_mov_b32_e32 v16, 0
	v_mov_b32_e32 v17, v113
	v_mov_b32_e32 v18, v113
	v_mov_b32_e32 v19, v113
	v_mov_b32_e32 v20, v113
	v_mov_b32_e32 v21, v113
	v_mov_b32_e32 v22, v113
	v_mov_b32_e32 v23, v113
	v_mov_b32_e32 v24, v113
	v_mov_b32_e32 v25, v113
	v_mov_b32_e32 v26, v113
	v_mov_b32_e32 v27, v113
	v_mov_b32_e32 v28, v113
	v_mov_b32_e32 v29, v113
	v_mov_b32_e32 v30, v113
	v_mov_b32_e32 v31, v113
	v_mov_b32_e32 v32, 0
	v_mov_b32_e32 v33, v113
	v_mov_b32_e32 v34, v113
	v_mov_b32_e32 v35, v113
	v_mov_b32_e32 v36, v113
	v_mov_b32_e32 v37, v113
	v_mov_b32_e32 v38, v113
	v_mov_b32_e32 v39, v113
	v_mov_b32_e32 v40, v113
	v_mov_b32_e32 v41, v113
	v_mov_b32_e32 v42, v113
	v_mov_b32_e32 v43, v113
	v_mov_b32_e32 v44, v113
	v_mov_b32_e32 v45, v113
	v_mov_b32_e32 v46, v113
	v_mov_b32_e32 v47, v113
	ds_write_b128 v159, v[94:97] offset:6656
	v_mov_b32_e32 v0, v1
	v_mov_b32_e32 v2, v1
	v_mov_b32_e32 v3, v1
	v_mov_b32_e32 v4, v1
	v_mov_b32_e32 v5, v1
	v_mov_b32_e32 v6, v1
	v_mov_b32_e32 v7, v1
	v_mov_b32_e32 v8, v1
	v_mov_b32_e32 v9, v1
	v_mov_b32_e32 v10, v1
	v_mov_b32_e32 v11, v1
	v_mov_b32_e32 v12, v1
	v_mov_b32_e32 v13, v1
	v_mov_b32_e32 v14, v1
	v_mov_b32_e32 v15, v1
	v_mov_b32_e32 v188, v1
	v_mov_b32_e32 v189, v1
	s_waitcnt lgkmcnt(0)
	s_barrier
.LBB0_373:
	s_bitcmp1_b32 s17, 0
	s_cselect_b32 s2, 0x2e00, 0
	s_add_i32 s2, s18, s2
	v_add3_u32 v191, s2, v153, v154
	ds_read_b128 v[132:135], v191
	ds_read_b128 v[136:139], v191 offset:32
	ds_read_b128 v[140:143], v191 offset:64
	ds_read_b128 v[160:163], v191 offset:96
	ds_read_b128 v[164:167], v191 offset:128
	ds_read_b128 v[168:171], v191 offset:160
	v_add3_u32 v191, s2, v102, v155
	v_add_u32_e32 v192, 0x1800, v191
	v_add_u32_e32 v191, 0x2000, v191
	ds_read2_b64 v[172:175], v192 offset0:64 offset1:66
	ds_read2_b64 v[176:179], v192 offset0:68 offset1:70
	ds_read2_b64 v[180:183], v191 offset0:128 offset1:130
	ds_read2_b64 v[184:187], v191 offset0:132 offset1:134
	s_add_i32 s2, s19, s17
	s_cmp_lt_i32 s2, 63
	s_cselect_b32 s2, s13, s45
	s_add_i32 s2, s16, s2
	v_add_u32_e32 v191, s2, v145
	v_mad_i64_i32 v[192:193], s[14:15], v191, s48, v[64:65]
	global_load_dwordx4 v[98:101], v[192:193], off
	s_and_saveexec_b64 s[14:15], s[0:1]
	s_cbranch_execz .LBB0_375
	v_add_u32_e32 v191, s2, v146
	v_mad_i64_i32 v[192:193], s[34:35], v191, s48, v[128:129]
	global_load_dwordx4 v[66:69], v[192:193], off
.LBB0_375:
	s_or_b64 exec, exec, s[14:15]
	s_add_i32 s14, s17, 1
	s_ashr_i32 s3, s2, 31
	v_lshl_add_u64 v[192:193], s[2:3], 1, v[130:131]
	global_load_dwordx4 v[94:97], v[192:193], off
	s_bitcmp1_b32 s14, 0
	s_cselect_b32 s2, 0x2e00, 0
	s_waitcnt lgkmcnt(9)
	v_mfma_f32_32x32x16_bf16 v[48:63], v[132:135], v[70:73], 0
	v_add_f32_e32 v2, v3, v2
	v_add_f32_e32 v2, v4, v2
	v_add_f32_e32 v2, v5, v2
	s_add_i32 s15, s18, s2
	s_waitcnt lgkmcnt(8)
	v_mfma_f32_32x32x16_bf16 v[48:63], v[136:139], v[74:77], v[48:63]
	v_add_f32_e32 v2, v6, v2
	v_add_f32_e32 v2, v7, v2
	v_add_f32_e32 v2, v8, v2
	s_waitcnt lgkmcnt(7)
	v_mfma_f32_32x32x16_bf16 v[48:63], v[140:143], v[78:81], v[48:63]
	v_add_f32_e32 v2, v9, v2
	v_add_f32_e32 v2, v10, v2
	v_add_f32_e32 v2, v11, v2
	s_waitcnt lgkmcnt(6)
	v_mfma_f32_32x32x16_bf16 v[48:63], v[160:163], v[82:85], v[48:63]
	v_add_f32_e32 v2, v12, v2
	v_add_f32_e32 v2, v13, v2
	v_add_f32_e32 v2, v14, v2
	s_waitcnt lgkmcnt(5)
	v_mfma_f32_32x32x16_bf16 v[48:63], v[164:167], v[86:89], v[48:63]
	v_add_f32_e32 v2, v15, v2
	v_add_f32_e32 v2, v188, v2
	v_add_f32_e32 v190, v189, v2
	s_waitcnt lgkmcnt(4)
	v_mfma_f32_32x32x16_bf16 v[48:63], v[168:171], v[90:93], v[48:63]
	v_fmac_f32_e32 v190, v113, v0
	v_mov_b32_e32 v113, v190
	s_nop 9
	v_max_f32_e32 v0, v49, v49
	v_max_f32_e32 v2, v48, v48
	v_max_f32_e32 v0, v2, v0
	v_max3_f32 v0, v0, v50, v51
	v_max3_f32 v0, v0, v52, v53
	v_max3_f32 v0, v0, v54, v55
	v_max3_f32 v0, v0, v56, v57
	v_max3_f32 v0, v0, v58, v59
	v_max3_f32 v0, v0, v60, v61
	v_max3_f32 v0, v0, v62, v63
	v_mov_b32_e32 v2, v0
	s_nop 1
	v_permlane32_swap_b32_e32 v2, v0
	s_nop 1
	v_max3_f32 v115, v117, v0, v2
	v_sub_f32_e32 v0, v117, v115
	v_sub_f32_e32 v2, v48, v115
	v_sub_f32_e32 v3, v49, v115
	v_sub_f32_e32 v4, v50, v115
	v_sub_f32_e32 v5, v51, v115
	v_sub_f32_e32 v6, v52, v115
	v_sub_f32_e32 v7, v53, v115
	v_sub_f32_e32 v8, v54, v115
	v_sub_f32_e32 v9, v55, v115
	v_exp_f32_e32 v2, v2
	v_exp_f32_e32 v3, v3
	v_exp_f32_e32 v4, v4
	v_exp_f32_e32 v5, v5
	v_exp_f32_e32 v6, v6
	v_exp_f32_e32 v7, v7
	v_exp_f32_e32 v8, v8
	v_exp_f32_e32 v9, v9
	v_exp_f32_e32 v0, v0
	v_cvt_pk_bf16_f32 v48, v2, v3
	v_cvt_pk_bf16_f32 v49, v4, v5
	v_cvt_pk_bf16_f32 v50, v6, v7
	v_pk_mul_f32 v[46:47], v[46:47], v[0:1] op_sel_hi:[1,0]
	v_pk_mul_f32 v[44:45], v[44:45], v[0:1] op_sel_hi:[1,0]
	v_pk_mul_f32 v[42:43], v[42:43], v[0:1] op_sel_hi:[1,0]
	v_pk_mul_f32 v[40:41], v[40:41], v[0:1] op_sel_hi:[1,0]
	v_pk_mul_f32 v[38:39], v[38:39], v[0:1] op_sel_hi:[1,0]
	v_pk_mul_f32 v[36:37], v[36:37], v[0:1] op_sel_hi:[1,0]
	v_pk_mul_f32 v[34:35], v[34:35], v[0:1] op_sel_hi:[1,0]
	v_pk_mul_f32 v[32:33], v[32:33], v[0:1] op_sel_hi:[1,0]
	v_pk_mul_f32 v[30:31], v[30:31], v[0:1] op_sel_hi:[1,0]
	v_cvt_pk_bf16_f32 v51, v8, v9
	v_pk_mul_f32 v[28:29], v[28:29], v[0:1] op_sel_hi:[1,0]
	v_pk_mul_f32 v[26:27], v[26:27], v[0:1] op_sel_hi:[1,0]
	v_pk_mul_f32 v[24:25], v[24:25], v[0:1] op_sel_hi:[1,0]
	v_pk_mul_f32 v[22:23], v[22:23], v[0:1] op_sel_hi:[1,0]
	v_pk_mul_f32 v[20:21], v[20:21], v[0:1] op_sel_hi:[1,0]
	v_pk_mul_f32 v[18:19], v[18:19], v[0:1] op_sel_hi:[1,0]
	v_pk_mul_f32 v[16:17], v[16:17], v[0:1] op_sel_hi:[1,0]
	s_waitcnt lgkmcnt(0)
	v_mfma_f32_32x32x16_bf16 v[32:47], v[172:175], v[48:51], v[32:47]
	v_sub_f32_e32 v10, v56, v115
	v_sub_f32_e32 v11, v57, v115
	v_sub_f32_e32 v12, v58, v115
	v_sub_f32_e32 v13, v59, v115
	v_sub_f32_e32 v14, v60, v115
	v_sub_f32_e32 v15, v61, v115
	v_sub_f32_e32 v52, v62, v115
	v_mfma_f32_32x32x16_bf16 v[16:31], v[180:183], v[48:51], v[16:31]
	v_add3_u32 v191, s15, v148, v149
	s_waitcnt vmcnt(0)
	ds_write_b128 v191, v[98:101]
	s_and_saveexec_b64 s[2:3], s[0:1]
	v_add3_u32 v191, s15, v150, v156
	ds_write_b128 v191, v[66:69]
	s_or_b64 exec, exec, s[2:3]
	v_add3_u32 v191, s15, v151, v152
	ds_write_b128 v191, v[94:97] offset:6656
	v_sub_f32_e32 v49, v63, v115
	v_exp_f32_e32 v10, v10
	v_exp_f32_e32 v11, v11
	v_exp_f32_e32 v12, v12
	v_exp_f32_e32 v13, v13
	v_exp_f32_e32 v14, v14
	v_exp_f32_e32 v15, v15
	v_exp_f32_e32 v188, v52
	v_exp_f32_e32 v189, v49
	v_cvt_pk_bf16_f32 v50, v10, v11
	v_cvt_pk_bf16_f32 v51, v12, v13
	v_cvt_pk_bf16_f32 v52, v14, v15
	v_cvt_pk_bf16_f32 v53, v188, v189
	s_nop 1
	v_mfma_f32_32x32x16_bf16 v[32:47], v[176:179], v[50:53], v[32:47]
	v_mfma_f32_32x32x16_bf16 v[16:31], v[184:187], v[50:53], v[16:31]
	s_add_i32 s16, s16, 32
	s_cmp_eq_u32 s14, 39
	s_waitcnt lgkmcnt(0)
	s_barrier
	s_cbranch_scc1 .LBB0_379
	v_mov_b32_e32 v117, v115
	s_mov_b32 s17, s14
	s_branch .LBB0_373
.LBB0_379:
	v_add_f32_e32 v2, v3, v2
	v_add_f32_e32 v2, v4, v2
	v_add_f32_e32 v2, v5, v2
	v_add_f32_e32 v2, v6, v2
	v_add_f32_e32 v2, v7, v2
	v_add_f32_e32 v2, v8, v2
	v_add_f32_e32 v2, v9, v2
	v_add_f32_e32 v2, v10, v2
	v_add_f32_e32 v2, v11, v2
	v_add_f32_e32 v2, v12, v2
	v_add_f32_e32 v2, v13, v2
	v_add_f32_e32 v2, v14, v2
	v_add_f32_e32 v2, v15, v2
	v_add_f32_e32 v2, v188, v2
	v_add_f32_e32 v98, v189, v2
	v_fmac_f32_e32 v98, v113, v0
	v_add3_u32 v0, s15, v153, v154
	ds_read_b128 v[94:97], v0
	ds_read_b128 v[128:131], v0 offset:32
	ds_read_b128 v[132:135], v0 offset:64
	ds_read_b128 v[136:139], v0 offset:96
	ds_read_b128 v[140:143], v0 offset:128
	ds_read_b128 v[160:163], v0 offset:160
	v_add3_u32 v0, s15, v102, v155
	v_add_u32_e32 v2, 0x1800, v0
	v_add_u32_e32 v0, 0x2000, v0
	v_mov_b32_e32 v14, v1
	v_mov_b32_e32 v15, v1
	ds_read2_b64 v[164:167], v2 offset0:64 offset1:66
	ds_read2_b64 v[64:67], v2 offset0:68 offset1:70
	ds_read2_b64 v[168:171], v0 offset0:128 offset1:130
	ds_read2_b64 v[172:175], v0 offset0:132 offset1:134
	v_mov_b32_e32 v0, v1
	v_mov_b32_e32 v2, v1
	v_mov_b32_e32 v3, v1
	v_mov_b32_e32 v4, v1
	v_mov_b32_e32 v5, v1
	v_mov_b32_e32 v6, v1
	v_mov_b32_e32 v7, v1
	v_mov_b32_e32 v8, v1
	v_mov_b32_e32 v9, v1
	v_mov_b32_e32 v10, v1
	v_mov_b32_e32 v11, v1
	v_mov_b32_e32 v12, v1
	v_mov_b32_e32 v13, v1
	v_mov_b64_e32 v[62:63], v[14:15]
	v_mov_b64_e32 v[60:61], v[12:13]
	v_mov_b64_e32 v[58:59], v[10:11]
	v_mov_b64_e32 v[56:57], v[8:9]
	v_mov_b64_e32 v[54:55], v[6:7]
	v_mov_b64_e32 v[52:53], v[4:5]
	v_mov_b64_e32 v[50:51], v[2:3]
	v_mov_b64_e32 v[48:49], v[0:1]
	s_andn2_b64 vcc, exec, s[8:9]
	s_waitcnt lgkmcnt(0)
	v_mfma_f32_32x32x16_bf16 v[48:63], v[94:97], v[70:73], v[48:63]
	s_barrier
	v_mfma_f32_32x32x16_bf16 v[48:63], v[128:131], v[74:77], v[48:63]
	v_mfma_f32_32x32x16_bf16 v[48:63], v[132:135], v[78:81], v[48:63]
	v_mfma_f32_32x32x16_bf16 v[48:63], v[136:139], v[82:85], v[48:63]
	v_mfma_f32_32x32x16_bf16 v[48:63], v[140:143], v[86:89], v[48:63]
	v_mfma_f32_32x32x16_bf16 v[48:63], v[160:163], v[90:93], v[48:63]
	s_nop 11
	v_max_f32_e32 v0, v49, v49
	v_max_f32_e32 v2, v48, v48
	v_max_f32_e32 v0, v2, v0
	v_max3_f32 v0, v0, v50, v51
	v_max3_f32 v0, v0, v52, v53
	v_max3_f32 v0, v0, v54, v55
	v_max3_f32 v0, v0, v56, v57
	v_max3_f32 v0, v0, v58, v59
	v_max3_f32 v0, v0, v60, v61
	v_max3_f32 v0, v0, v62, v63
	v_mov_b32_e32 v2, v0
	s_nop 1
	v_permlane32_swap_b32_e32 v2, v0
	s_nop 1
	v_max3_f32 v0, v115, v0, v2
	v_sub_f32_e32 v3, v48, v0
	v_sub_f32_e32 v4, v49, v0
	v_exp_f32_e32 v3, v3
	v_sub_f32_e32 v5, v50, v0
	v_exp_f32_e32 v4, v4
	v_sub_f32_e32 v6, v51, v0
	v_exp_f32_e32 v5, v5
	v_sub_f32_e32 v2, v115, v0
	v_sub_f32_e32 v7, v52, v0
	v_sub_f32_e32 v10, v55, v0
	v_exp_f32_e32 v6, v6
	v_sub_f32_e32 v8, v53, v0
	v_exp_f32_e32 v7, v7
	v_exp_f32_e32 v49, v10
	v_exp_f32_e32 v10, v2
	v_add_f32_e32 v2, 0, v3
	v_sub_f32_e32 v9, v54, v0
	v_exp_f32_e32 v8, v8
	v_add_f32_e32 v2, v4, v2
	v_exp_f32_e32 v9, v9
	v_add_f32_e32 v2, v5, v2
	v_sub_f32_e32 v11, v56, v0
	v_add_f32_e32 v2, v6, v2
	v_sub_f32_e32 v12, v57, v0
	v_exp_f32_e32 v11, v11
	v_add_f32_e32 v2, v7, v2
	v_exp_f32_e32 v12, v12
	v_add_f32_e32 v2, v8, v2
	v_add_f32_e32 v2, v9, v2
	v_add_f32_e32 v2, v49, v2
	v_add_f32_e32 v2, v11, v2
	v_add_f32_e32 v50, v12, v2
	v_pk_mul_f32 v[46:47], v[46:47], v[10:11] op_sel_hi:[1,0]
	v_pk_mul_f32 v[44:45], v[44:45], v[10:11] op_sel_hi:[1,0]
	v_pk_mul_f32 v[42:43], v[42:43], v[10:11] op_sel_hi:[1,0]
	v_pk_mul_f32 v[40:41], v[40:41], v[10:11] op_sel_hi:[1,0]
	v_pk_mul_f32 v[38:39], v[38:39], v[10:11] op_sel_hi:[1,0]
	v_pk_mul_f32 v[36:37], v[36:37], v[10:11] op_sel_hi:[1,0]
	v_pk_mul_f32 v[34:35], v[34:35], v[10:11] op_sel_hi:[1,0]
	v_pk_mul_f32 v[32:33], v[32:33], v[10:11] op_sel_hi:[1,0]
	v_pk_mul_f32 v[30:31], v[30:31], v[10:11] op_sel_hi:[1,0]
	v_cvt_pk_bf16_f32 v2, v3, v4
	v_cvt_pk_bf16_f32 v3, v5, v6
	v_cvt_pk_bf16_f32 v4, v7, v8
	v_cvt_pk_bf16_f32 v5, v9, v49
	v_pk_mul_f32 v[28:29], v[28:29], v[10:11] op_sel_hi:[1,0]
	v_pk_mul_f32 v[26:27], v[26:27], v[10:11] op_sel_hi:[1,0]
	v_pk_mul_f32 v[24:25], v[24:25], v[10:11] op_sel_hi:[1,0]
	v_pk_mul_f32 v[22:23], v[22:23], v[10:11] op_sel_hi:[1,0]
	v_pk_mul_f32 v[20:21], v[20:21], v[10:11] op_sel_hi:[1,0]
	v_pk_mul_f32 v[18:19], v[18:19], v[10:11] op_sel_hi:[1,0]
	v_pk_mul_f32 v[16:17], v[16:17], v[10:11] op_sel_hi:[1,0]
	s_waitcnt lgkmcnt(0)
	v_mfma_f32_32x32x16_bf16 v[32:47], v[164:167], v[2:5], v[32:47]
	v_sub_f32_e32 v13, v58, v0
	v_sub_f32_e32 v14, v59, v0
	v_sub_f32_e32 v15, v60, v0
	v_sub_f32_e32 v48, v61, v0
	v_sub_f32_e32 v51, v62, v0
	v_exp_f32_e32 v13, v13
	v_exp_f32_e32 v14, v14
	v_mfma_f32_32x32x16_bf16 v[16:31], v[168:171], v[2:5], v[16:31]
	v_sub_f32_e32 v3, v63, v0
	v_exp_f32_e32 v15, v15
	v_exp_f32_e32 v48, v48
	v_exp_f32_e32 v2, v51
	v_exp_f32_e32 v3, v3
	v_cvt_pk_bf16_f32 v6, v11, v12
	v_cvt_pk_bf16_f32 v7, v13, v14
	v_cvt_pk_bf16_f32 v8, v15, v48
	v_cvt_pk_bf16_f32 v9, v2, v3
	v_add_f32_e32 v4, v13, v50
	v_add_f32_e32 v4, v14, v4
	v_mfma_f32_32x32x16_bf16 v[32:47], v[64:67], v[6:9], v[32:47]
	v_add_f32_e32 v4, v15, v4
	v_add_f32_e32 v4, v48, v4
	v_add_f32_e32 v2, v2, v4
	v_add_f32_e32 v4, v3, v2
	v_fmac_f32_e32 v4, v98, v10
	v_mfma_f32_32x32x16_bf16 v[16:31], v[172:175], v[6:9], v[16:31]
	s_cbranch_vccnz .LBB0_381
	s_nop 4
	ds_write2st64_b32 v123, v32, v33 offset0:192 offset1:193
	s_nop 4
	ds_write2st64_b32 v123, v16, v17 offset0:208 offset1:209
	ds_write2st64_b32 v123, v34, v35 offset0:194 offset1:195
	ds_write2st64_b32 v123, v18, v19 offset0:210 offset1:211
	ds_write2st64_b32 v123, v36, v37 offset0:196 offset1:197
	ds_write2st64_b32 v123, v20, v21 offset0:212 offset1:213
	ds_write2st64_b32 v123, v38, v39 offset0:198 offset1:199
	ds_write2st64_b32 v123, v22, v23 offset0:214 offset1:215
	ds_write2st64_b32 v123, v40, v41 offset0:200 offset1:201
	ds_write2st64_b32 v123, v24, v25 offset0:216 offset1:217
	ds_write2st64_b32 v123, v42, v43 offset0:202 offset1:203
	ds_write2st64_b32 v123, v26, v27 offset0:218 offset1:219
	ds_write2st64_b32 v123, v44, v45 offset0:204 offset1:205
	ds_write2st64_b32 v123, v28, v29 offset0:220 offset1:221
	ds_write2st64_b32 v123, v46, v47 offset0:206 offset1:207
	ds_write2st64_b32 v123, v30, v31 offset0:222 offset1:223
	ds_write2st64_b32 v123, v0, v4 offset0:224 offset1:225
